# k26: scan loader DMA block tightened (m0 written directly, incremental ring-slot offset, no s_nop padding: 28 fewer scalar instructions per step)
# speedup vs baseline: 1.0050x; 1.0029x over previous
.LBB0_812:
	s_and_b64 vcc, exec, s[46:47]
	s_cbranch_vccz .LBB0_841
	v_and_b32_e32 v0, 31, v128
	v_lshrrev_b32_e32 v1, 5, v148
	s_cmp_lt_u32 s61, 64
	v_mul_u32_u24_e32 v76, 0x90, v0
	v_lshlrev_b32_e32 v77, 3, v1
	v_mul_u32_u24_e32 v78, 24, v0
	v_and_b32_e32 v79, 32, v128
	v_lshlrev_b32_e32 v81, 9, v1
	s_mov_b64 s[4:5], -1
	v_lshlrev_b32_e32 v80, 5, v0
	v_lshlrev_b32_e32 v82, 2, v0
	s_cbranch_scc1 .LBB0_831
	s_add_i32 s4, 0, 0x17c00
	s_lshl_b32 s12, s42, 6
	s_lshl_b32 s10, s42, 4
	v_add3_u32 v83, s4, v81, v82
	s_lshl_b64 s[4:5], s[0:1], 21
	v_lshlrev_b32_e32 v0, 4, v148
	v_mov_b32_e32 v8, 0
	s_add_u32 s4, s92, s4
	v_and_b32_e32 v2, 48, v0
	v_lshlrev_b32_e32 v0, 8, v148
	v_mov_b32_e32 v1, v8
	s_addc_u32 s5, s93, s5
	v_lshl_add_u64 v[68:69], s[4:5], 0, v[0:1]
	s_lshl_b64 s[4:5], s[0:1], 23
	v_and_b32_e32 v1, 0x3c00, v0
	v_or_b32_e32 v1, s4, v1
	v_or3_b32 v2, v1, s12, v2
	s_lshl_b64 s[0:1], s[0:1], 24
	v_and_b32_e32 v0, 0x3800, v0
	v_and_b32_e32 v1, 7, v128
	v_mov_b32_e32 v3, s5
	v_or_b32_e32 v0, s0, v0
	s_lshl_b32 s0, s42, 7
	v_lshlrev_b32_e32 v1, 4, v1
	v_readlane_b32 s12, v254, 0
	v_lshl_add_u64 v[2:3], s[92:93], 0, v[2:3]
	s_mov_b64 s[4:5], 0x17b10000
	v_or3_b32 v0, v0, s0, v1
	v_mov_b32_e32 v1, s1
	v_readlane_b32 s18, v254, 6
	v_readlane_b32 s19, v254, 7
	v_mov_b32_e32 v14, v8
	v_mov_b32_e32 v15, v8
	v_lshl_add_u64 v[70:71], v[2:3], 0, s[4:5]
	v_lshl_add_u64 v[72:73], s[92:93], 0, v[0:1]
	v_readlane_b32 s13, v254, 1
	v_readlane_b32 s14, v254, 2
	v_readlane_b32 s15, v254, 3
	v_readlane_b32 s16, v254, 4
	v_readlane_b32 s17, v254, 5
	v_lshl_add_u64 v[74:75], s[18:19], 0, v[0:1]
	v_mov_b32_e32 v0, v8
	v_mov_b32_e32 v1, v8
	v_mov_b32_e32 v2, v8
	v_mov_b32_e32 v3, v8
	v_mov_b32_e32 v4, v8
	v_mov_b32_e32 v5, v8
	v_mov_b32_e32 v6, v8
	v_mov_b32_e32 v7, v8
	v_mov_b32_e32 v9, v8
	v_mov_b32_e32 v10, v8
	v_mov_b32_e32 v11, v8
	v_mov_b32_e32 v12, v8
	v_mov_b32_e32 v13, v8
	v_mov_b64_e32 v[30:31], v[14:15]
	v_mov_b64_e32 v[46:47], v[14:15]
	v_cmp_gt_u32_e64 s[6:7], 32, v148
	s_mov_b32 s33, 4
	v_cmp_gt_u32_e64 s[8:9], 16, v148
	s_mov_b32 s11, 0
	s_mov_b64 s[0:1], 0x2204000
	s_mov_b64 s[12:13], 0
	s_mov_b64 s[14:15], 0x37f20000
	s_mov_b64 s[16:17], 0x37f24000
	s_mov_b64 s[18:19], 0x20000
	s_mov_b64 s[20:21], 0x24000
	s_mov_b64 s[22:23], 0x8020000
	s_mov_b64 s[24:25], 0x8024000
	s_mov_b64 s[26:27], 0xfa20000
	s_mov_b64 s[28:29], 0xfa24000
	s_mov_b64 s[30:31], 0x2000
	s_mov_b64 s[34:35], 0x4000
	v_mov_b64_e32 v[28:29], v[12:13]
	v_mov_b64_e32 v[26:27], v[10:11]
	v_mov_b64_e32 v[24:25], v[8:9]
	v_mov_b64_e32 v[22:23], v[6:7]
	v_mov_b64_e32 v[20:21], v[4:5]
	v_mov_b64_e32 v[18:19], v[2:3]
	v_mov_b64_e32 v[16:17], v[0:1]
	v_mov_b64_e32 v[44:45], v[12:13]
	v_mov_b64_e32 v[42:43], v[10:11]
	v_mov_b64_e32 v[40:41], v[8:9]
	v_mov_b64_e32 v[38:39], v[6:7]
	v_mov_b64_e32 v[36:37], v[4:5]
	v_mov_b64_e32 v[34:35], v[2:3]
	v_mov_b64_e32 v[32:33], v[0:1]
	v_readfirstlane_b32 s64, v72
	v_readfirstlane_b32 s65, v73
	v_readfirstlane_b32 s66, v74
	v_readfirstlane_b32 s67, v75
	v_readfirstlane_b32 s68, v70
	v_readfirstlane_b32 s69, v71
	v_readfirstlane_b32 s70, v68
	v_readfirstlane_b32 s71, v69
	s_nop 1
	v_subrev_u32_e32 v102, s64, v72
	v_subrev_u32_e32 v103, s66, v74
	v_subrev_u32_e32 v104, s68, v70
	v_subrev_u32_e32 v105, s70, v68
	s_mov_b32 s78, 0xa400
	s_branch .LBB0_817

.LBB0_826:
	s_add_i32 s36, s78, 0x19c00
	s_add_u32 s72, s64, s12
	s_addc_u32 s73, s65, s13
	s_add_u32 s76, s66, s12
	s_addc_u32 s77, s67, s13
	s_mov_b32 m0, s36
	s_add_u32 s74, s72, s14
	s_addc_u32 s75, s73, s15
	global_load_lds_dwordx4 v102, s[74:75]
	s_add_i32 m0, s36, 0x400
	s_add_u32 s74, s72, s16
	s_addc_u32 s75, s73, s17
	global_load_lds_dwordx4 v102, s[74:75]
	s_add_i32 m0, s36, 0x800
	s_add_u32 s74, s76, s18
	s_addc_u32 s75, s77, s19
	global_load_lds_dwordx4 v103, s[74:75]
	s_add_i32 m0, s36, 0xc00
	s_add_u32 s74, s76, s20
	s_addc_u32 s75, s77, s21
	global_load_lds_dwordx4 v103, s[74:75]
	s_add_i32 m0, s36, 0x1000
	s_add_u32 s74, s76, s22
	s_addc_u32 s75, s77, s23
	global_load_lds_dwordx4 v103, s[74:75]
	s_add_i32 m0, s36, 0x1400
	s_add_u32 s74, s76, s24
	s_addc_u32 s75, s77, s25
	global_load_lds_dwordx4 v103, s[74:75]
	s_add_i32 m0, s36, 0x1800
	s_add_u32 s74, s72, s26
	s_addc_u32 s75, s73, s27
	global_load_lds_dwordx4 v102, s[74:75]
	s_add_i32 m0, s36, 0x1c00
	s_add_u32 s74, s72, s28
	s_addc_u32 s75, s73, s29
	global_load_lds_dwordx4 v102, s[74:75]
	s_add_i32 s78, s78, 0x2900
	s_cmp_eq_u32 s78, 0xcd00
	s_cselect_b32 s78, 0, s78
	s_and_saveexec_b64 s[4:5], s[6:7]
	s_cbranch_execz .LBB0_828
	s_add_i32 m0, s36, 0x2000
	s_add_u32 s74, s68, s30
	s_addc_u32 s75, s69, s31
	global_load_lds_dwordx4 v104, s[68:69]
	s_add_i32 m0, s36, 0x2200
	s_nop 0
	global_load_lds_dwordx4 v104, s[74:75]
.LBB0_828:
	s_or_b64 exec, exec, s[4:5]
	s_and_saveexec_b64 s[4:5], s[8:9]
	s_cbranch_execz .LBB0_815
	s_add_i32 m0, s36, 0x2800
	s_add_u32 s74, s70, s0
	s_addc_u32 s75, s71, s1
	s_add_u32 s74, s74, s10
	s_addc_u32 s75, s75, s11
	global_load_lds_dwordx4 v105, s[74:75]
	s_branch .LBB0_815
